# adds one static s_setprio 1 for waves 4-7 during the attention loop; S5 half-loop waits count past the previous half's stores
# baseline (speedup 1.0000x reference)
; __device__ __forceinline__ int fresh_lane() { int l; asm volatile("v_mbcnt_lo_u32_b32 %0, -1, 0\n\tv_mbcnt_hi_u32_b32 %0, -1, %0" : "=v"(l)); return l; }
; __device__ __forceinline__ void attn_phase(LAS unsigned char* lds, const bf16* PROJ, bf16* MIX, const float* lq1, const float* lk1, const float* lq2, const float* lk2,
;                                            const float* norm_g, float lambda_init, int G, int wave_s) {
;     int tid_ = wave_s * 64 + fresh_lane(); asm volatile("" : "+v"(tid_)); const int tid = tid_, lane = tid & 63, w = __builtin_amdgcn_readfirstlane(tid >> 6), q4 = lane >> 4, l15 = lane & 15, mi = w >> 2, wq = w & 3;
;     float lam;
;     { float s1 = lq1[lane] * lk1[lane] + lq1[lane + 64] * lk1[lane + 64], s2 = lq2[lane] * lk2[lane] + lq2[lane + 64] * lk2[lane + 64];
;       s1 = wave_sum(s1); s2 = wave_sum(s2); lam = expf(s1) - expf(s2) + lambda_init; }
.LBB0_879:
	s_or_b64 exec, exec, s[10:11]
	s_load_dwordx8 s[40:47], s[8:9], 0xe8
	v_readlane_b32 s10, v254, 57
	v_readlane_b32 s11, v254, 58
	s_lshl_b32 s80, s10, 7
	s_lshl_b64 s[10:11], s[80:81], 2
	s_waitcnt lgkmcnt(0)
	s_add_u32 s16, s40, s10
	v_mbcnt_lo_u32_b32 v0, -1, 0
	v_mbcnt_hi_u32_b32 v0, -1, v0
	s_addc_u32 s17, s41, s11
	v_add_u32_e32 v2, s89, v0
	s_add_u32 s14, s42, s10
	v_and_b32_e32 v3, 63, v2
	v_lshlrev_b32_e32 v0, 2, v3
	s_addc_u32 s15, s43, s11
	global_load_dword v4, v0, s[16:17]
	global_load_dword v5, v0, s[14:15]
	global_load_dword v6, v0, s[16:17] offset:256
	global_load_dword v7, v0, s[14:15] offset:256
	s_add_u32 s12, s44, s10
	s_addc_u32 s13, s45, s11
	s_add_u32 s10, s46, s10
	s_addc_u32 s11, s47, s11
	v_readfirstlane_b32 s18, v2
	s_andn2_b64 vcc, exec, s[86:87]
	s_waitcnt vmcnt(0)
	v_mul_f32_e32 v6, v6, v7
	v_fmac_f32_e32 v6, v4, v5
	global_load_dword v4, v0, s[12:13]
	global_load_dword v5, v0, s[10:11]
	global_load_dword v7, v0, s[12:13] offset:256
	s_nop 0
	global_load_dword v0, v0, s[10:11] offset:256
	s_waitcnt vmcnt(0)
	v_mul_f32_e32 v0, v7, v0
	v_fmac_f32_e32 v0, v4, v5
	v_add_f32_dpp v4, v6, v6 row_ror:8 row_mask:0xf bank_mask:0xf bound_ctrl:1
	s_nop 0
	v_add_f32_dpp v0, v0, v0 row_ror:8 row_mask:0xf bank_mask:0xf bound_ctrl:1
	v_add_f32_dpp v4, v4, v4 row_ror:4 row_mask:0xf bank_mask:0xf bound_ctrl:1
	s_nop 0
	v_add_f32_dpp v0, v0, v0 row_ror:4 row_mask:0xf bank_mask:0xf bound_ctrl:1
	v_add_f32_dpp v4, v4, v4 row_ror:2 row_mask:0xf bank_mask:0xf bound_ctrl:1
	s_nop 0
	v_add_f32_dpp v0, v0, v0 row_ror:2 row_mask:0xf bank_mask:0xf bound_ctrl:1
	v_add_f32_dpp v4, v4, v4 row_ror:1 row_mask:0xf bank_mask:0xf bound_ctrl:1
	v_mov_b32_e32 v5, v4
	s_nop 1
	v_permlane16_swap_b32_e32 v4, v5
	v_add_f32_dpp v0, v0, v0 row_ror:1 row_mask:0xf bank_mask:0xf bound_ctrl:1
	v_add_f32_e32 v5, v4, v5
	v_mov_b32_e32 v4, v0
	s_nop 1
	v_permlane16_swap_b32_e32 v0, v4
	v_add_f32_e32 v0, v0, v4
	v_mov_b32_e32 v6, v5
	v_mov_b32_e32 v4, v0
	s_nop 0
	v_permlane32_swap_b32_e32 v5, v6
	v_permlane32_swap_b32_e32 v0, v4
	s_cbranch_vccnz .LBB0_906
; #define LAS __attribute__((address_space(3)))
; __device__ __forceinline__ void attn_phase(LAS unsigned char* lds, const bf16* PROJ, bf16* MIX, const float* lq1, const float* lk1, const float* lq2, const float* lk2,
;                                            const float* norm_g, float lambda_init, int G, int wave_s) {
;     int tid_ = wave_s * 64 + fresh_lane(); asm volatile("" : "+v"(tid_)); const int tid = tid_, lane = tid & 63, w = __builtin_amdgcn_readfirstlane(tid >> 6), q4 = lane >> 4, l15 = lane & 15, mi = w >> 2, wq = w & 3;
;     float lam;
;     { float s1 = lq1[lane] * lk1[lane] + lq1[lane + 64] * lk1[lane + 64], s2 = lq2[lane] * lk2[lane] + lq2[lane + 64] * lk2[lane + 64];
;       s1 = wave_sum(s1); s2 = wave_sum(s2); lam = expf(s1) - expf(s2) + lambda_init; }
;     LAS unsigned char* K0 = lds; LAS unsigned char* K1 = lds + 17408; LAS unsigned char* VT = lds + 34816; LAS unsigned char* XCH = lds;
;     LAS unsigned char* Kmine = mi ? K1 : K0;
;     const LAS unsigned char* vtr0 = VT + (4 * q4 + (l15 >> 2)) * 544 + (l15 & 3) * 8;
;     const float c1 = 0.08838834764831845f * LOG2E;
;     unsigned offK[2], offV[4];
; #pragma unroll
;     for (int j = 0; j < 2; ++j) { const int c = tid + 512 * j; offK[j] = (unsigned)((c >> 4) * PLD + 4096 + 8 * (c & 15)) * 2u; }
; #pragma unroll
;     for (int j = 0; j < 4; ++j) { const int c = tid + 512 * j; offV[j] = (unsigned)((c >> 5) * PLD + 5120 + 8 * (c & 31)) * 2u; }
;     for (int u0 = blockIdx.x; u0 < 256; u0 += G) {
;         const int u = (G == 256) ? (((u0 & 7) << 5) | (u0 >> 3)) : u0;
;         const int b = u >> 6, h = (u >> 4) & 3, p = u & 15;
;         const float sl2 = exp2f(-2.0f * (float)(h + 1)) * LOG2E;
;         const bf16* base = PROJ + (size_t)b * SEQ * PLD;
;         for (int half = 0; half < 2; ++half) {
;             const int qb = half ? 31 - p : p;
;             const int qloc = 16 * wq + l15;
;             bf16x8 qf[4];
;             { const bf16* qp = base + (size_t)(64 * qb + qloc) * PLD + 3072 + h * 256 + mi * 128 + 8 * q4;
; #pragma unroll
;               for (int sk = 0; sk < 4; ++sk) qf[sk] = *(const bf16x8*)(qp + 32 * sk); }
;             f32x4 O[16];
; #pragma unroll
;             for (int mt = 0; mt < 16; ++mt) O[mt] = (f32x4){0.f, 0.f, 0.f, 0.f};
;             float m_run = -1e30f, l_part = 0.f;
	s_load_dwordx2 s[8:9], s[8:9], 0x108
	v_readlane_b32 s10, v254, 57
	v_readlane_b32 s11, v254, 58
	s_lshl_b32 s80, s10, 8
	v_lshrrev_b32_e32 v7, 4, v3
	s_lshl_b64 s[10:11], s[80:81], 2
	s_waitcnt lgkmcnt(0)
	s_add_u32 s8, s8, s10
	v_lshlrev_b32_e32 v9, 2, v7
	v_bfe_u32 v10, v2, 2, 2
	s_addc_u32 s9, s9, s11
	v_readlane_b32 s10, v254, 53
	v_or_b32_e32 v10, v9, v10
	v_lshlrev_b32_e32 v11, 3, v2
	s_cmp_eq_u32 s10, 1
	v_mul_u32_u24_e32 v10, 0x220, v10
	v_and_b32_e32 v12, 24, v11
	s_cselect_b64 vcc, -1, 0
	v_add3_u32 v162, 0, v10, v12
	v_mov_b32_e32 v10, 0x3f0e59d4
	v_mov_b32_e32 v12, 0x3eb60549
	v_cndmask_b32_e32 v10, v10, v12, vcc
	v_add_u32_e32 v12, 0x600, v2
	v_ashrrev_i32_e32 v12, 5, v12
	s_movk_i32 s16, 0x1800
	v_and_b32_e32 v14, 0xf8, v11
	v_mul_lo_u32 v13, v12, s16
	v_or_b32_e32 v14, 0x1400, v14
	v_add_lshl_u32 v138, v13, v14, 1
	v_add_u32_e32 v13, 0x400, v2
	v_ashrrev_i32_e32 v13, 5, v13
	v_mul_lo_u32 v15, v13, s16
	v_add_lshl_u32 v140, v15, v14, 1
	v_add_u32_e32 v15, 0x200, v2
	v_ashrrev_i32_e32 v16, 5, v15
	s_ashr_i32 s21, s18, 8
	v_mul_lo_u32 v17, v16, s16
	v_readlane_b32 s11, v254, 54
	s_cmpk_eq_i32 s37, 0x100
	v_add_lshl_u32 v142, v17, v14, 1
	v_ashrrev_i32_e32 v17, 5, v2
	s_cselect_b64 s[10:11], -1, 0
	s_lshr_b32 s19, s18, 2
	s_lshl_b32 s12, s21, 7
	v_mul_lo_u32 v18, v17, s16
	s_and_b32 s20, s19, 48
	s_ashr_i32 s13, s12, 31
	s_add_i32 s26, 0, 0x19800
	v_add_lshl_u32 v144, v14, v18, 1
	v_ashrrev_i32_e32 v14, 4, v15
	v_and_b32_e32 v11, 0x78, v11
	v_add_f32_e32 v5, v5, v6
	s_cmpk_lt_u32 s18, 0x100
	v_mul_lo_u32 v15, v14, s16
	v_or_b32_e32 v11, 0x1000, v11
	v_mul_f32_e32 v6, 0x3fb8aa3b, v5
	s_mov_b32 s18, 0x3fb8aa3b
	v_add_lshl_u32 v146, v15, v11, 1
	v_ashrrev_i32_e32 v15, 4, v2
	v_fma_f32 v19, v5, s18, -v6
	v_rndne_f32_e32 v20, v6
	v_add_f32_e32 v0, v0, v4
	v_mul_lo_u32 v18, v15, s16
	v_fmac_f32_e32 v19, 0x32a5705f, v5
	v_sub_f32_e32 v6, v6, v20
	v_mul_f32_e32 v4, 0x3fb8aa3b, v0
	v_add_f32_e32 v6, v6, v19
	v_add_lshl_u32 v148, v11, v18, 1
	v_fma_f32 v11, v0, s18, -v4
	v_rndne_f32_e32 v18, v4
	v_exp_f32_e32 v6, v6
	v_cvt_i32_f32_e32 v19, v20
	v_fmac_f32_e32 v11, 0x32a5705f, v0
	v_sub_f32_e32 v4, v4, v18
	v_add_f32_e32 v4, v4, v11
	s_cselect_b64 s[14:15], -1, 0
	v_exp_f32_e32 v4, v4
	v_cvt_i32_f32_e32 v11, v18
	s_and_b64 s[16:17], s[14:15], exec
	s_mov_b32 s18, 0xc2ce8ed0
	v_ldexp_f32 v6, v6, v19
	v_cmp_ngt_f32_e32 vcc, s18, v5
	s_mov_b32 s17, 0x42b17218
	v_ldexp_f32 v4, v4, v11
	v_cndmask_b32_e32 v6, 0, v6, vcc
	v_cmp_nlt_f32_e32 vcc, s17, v5
	v_readlane_b32 s16, v254, 34
	s_cselect_b32 s16, 0, s16
	v_cndmask_b32_e32 v5, v218, v6, vcc
	v_cmp_ngt_f32_e32 vcc, s18, v0
	v_readlane_b32 s18, v254, 36
	v_and_b32_e32 v8, 15, v2
	v_cndmask_b32_e32 v4, 0, v4, vcc
	v_cmp_nlt_f32_e32 vcc, s17, v0
	v_readlane_b32 s17, v254, 35
	v_lshl_add_u32 v170, v3, 4, 0
	v_cndmask_b32_e32 v0, v218, v4, vcc
	v_lshlrev_b32_e32 v4, 4, v2
	v_sub_f32_e32 v0, v5, v0
	v_and_b32_e32 v5, 0xf0, v4
	v_and_b32_e32 v4, 0x1f0, v4
	v_add_u32_e32 v165, 0, v4
	v_add_u32_e32 v169, s26, v4
	v_mov_b32_e32 v4, s16
	s_cselect_b32 s16, s17, s18
	v_add_u32_e32 v164, 0, v5
	v_add_u32_e32 v167, s17, v5
	v_add_u32_e32 v168, s18, v5
	v_and_b32_e32 v5, 48, v2
	v_mov_b32_e32 v2, s16
	v_mad_u32_u24 v6, v8, s5, v2
	v_and_b32_e32 v2, 48, v3
	v_mov_b32_e32 v3, v1
	v_or_b32_e32 v163, s20, v8
	v_lshl_add_u64 v[154:155], s[8:9], 0, v[2:3]
	v_or_b32_e32 v2, 2, v9
	v_cmp_gt_u32_e64 s[44:45], v2, v163
	v_or_b32_e32 v2, 3, v9
	v_cmp_gt_u32_e64 s[46:47], v2, v163
	v_or_b32_e32 v2, 16, v9
	v_cmp_gt_u32_e64 s[48:49], v2, v163
	v_or_b32_e32 v2, 17, v9
	v_cmp_gt_u32_e64 s[50:51], v2, v163
	v_or_b32_e32 v2, 18, v9
	v_cmp_gt_u32_e64 s[52:53], v2, v163
	v_or_b32_e32 v2, 19, v9
	v_cmp_gt_u32_e64 s[54:55], v2, v163
	v_or_b32_e32 v2, 32, v9
	v_cmp_gt_u32_e64 s[56:57], v2, v163
	v_or_b32_e32 v2, 33, v9
	v_cmp_gt_u32_e64 s[58:59], v2, v163
	v_or_b32_e32 v2, 34, v9
	v_cmp_gt_u32_e64 s[60:61], v2, v163
	v_or_b32_e32 v2, 35, v9
	v_cmp_gt_u32_e64 s[62:63], v2, v163
	v_or_b32_e32 v2, 48, v9
	v_cmp_gt_u32_e64 s[64:65], v2, v163
	v_or_b32_e32 v2, 49, v9
	v_add_f32_e32 v150, v10, v0
	v_lshlrev_b32_e32 v0, 3, v7
	s_cmp_eq_u32 s21, 1
	s_movk_i32 s8, 0x220
	v_cmp_gt_u32_e64 s[66:67], v2, v163
	v_or_b32_e32 v2, 50, v9
	v_mad_u32_u24 v4, v8, s5, v4
	s_cselect_b64 s[16:17], -1, 0
	v_mul_lo_u32 v174, v17, s8
	v_mul_lo_u32 v175, v16, s8
	v_mul_lo_u32 v176, v13, s8
	v_mul_lo_u32 v177, v12, s8
	v_cmp_gt_u32_e64 s[68:69], v2, v163
	v_or_b32_e32 v2, 51, v9
	s_lshl_b32 s8, s19, 10
	v_lshl_add_u64 v[156:157], s[0:1], 0, v[0:1]
	v_readlane_b32 s0, v253, 0
	s_mov_b32 s2, 0x3fb8aa3b
	s_mov_b32 s34, 0xc2ce8ed0
	s_mov_b32 s35, 0x42b17218
	v_cvt_f32_ubyte0_e32 v166, v9
	v_mov_b32_e32 v151, v150
	v_mov_b32_e32 v152, v150
	v_mov_b32_e32 v153, v150
	v_sub_f32_e32 v171, 1.0, v10
	v_mov_b32_e32 v149, v1
	v_mov_b32_e32 v147, v1
	v_mov_b32_e32 v145, v1
	v_mov_b32_e32 v143, v1
	v_mov_b32_e32 v141, v1
	v_mov_b32_e32 v139, v1
	v_mul_lo_u32 v172, v15, s5
	v_mul_lo_u32 v173, v14, s5
	v_cmp_gt_u32_e64 s[40:41], v9, v163
	v_cmp_ge_u32_e64 s[42:43], v9, v163
	v_cmp_gt_u32_e64 s[70:71], v2, v163
	v_add_u32_e32 v178, 0x1bb00, v162
	v_add_u32_e32 v179, 0x1dd00, v162
	v_add_u32_e32 v180, 0x1ff00, v162
	v_add_u32_e32 v181, 0x19920, v162
	v_add_u32_e32 v182, 0x1bb20, v162
	v_add_u32_e32 v183, 0x1dd20, v162
	v_add_u32_e32 v184, 0x1ff20, v162
	v_add_u32_e32 v185, 0x19940, v162
	v_add_u32_e32 v186, 0x1bb40, v162
	v_add_u32_e32 v187, 0x1dd40, v162
	v_add_u32_e32 v188, 0x1ff40, v162
	v_add_u32_e32 v189, 0x19960, v162
	v_add_u32_e32 v190, 0x1bb60, v162
	v_add_u32_e32 v191, 0x1dd60, v162
	v_add_u32_e32 v192, 0x1ff60, v162
	v_add_u32_e32 v193, 0x19980, v162
	v_add_u32_e32 v194, 0x1bb80, v162
	v_add_u32_e32 v195, 0x1dd80, v162
	v_add_u32_e32 v196, 0x1ff80, v162
	v_add_u32_e32 v197, 0x199a0, v162
	v_add_u32_e32 v198, 0x1bba0, v162
	v_add_u32_e32 v199, 0x1dda0, v162
	v_add_u32_e32 v200, 0x1ffa0, v162
	v_add_u32_e32 v201, 0x199c0, v162
	v_add_u32_e32 v202, 0x1bbc0, v162
	v_add_u32_e32 v203, 0x1ddc0, v162
	v_add_u32_e32 v204, 0x1ffc0, v162
	v_add_u32_e32 v205, 0x199e0, v162
	v_add_u32_e32 v206, 0x1bbe0, v162
	v_add_u32_e32 v207, 0x1dde0, v162
	v_add_u32_e32 v208, 0x1ffe0, v162
	s_lshl_b32 s72, s20, 10
	s_or_b32 s73, s8, 0x3c00
	v_lshlrev_b32_e32 v158, 1, v0
	v_add_u32_e32 v209, v4, v5
	v_add_u32_e32 v210, v6, v5
	s_mov_b32 s76, s0
	v_readlane_b32 s1, v253, 1
	s_cmpk_lt_u32 s89, 0x100
	s_cbranch_scc1 .Lattn_prio_done
	s_setprio 1
.Lattn_prio_done:
	s_branch .LBB0_882
.LBB0_881:
	s_add_i32 s76, s76, s37
	s_cmpk_gt_i32 s76, 0xff
	s_cbranch_scc1 .LBB0_905

; __device__ __forceinline__ void attn_phase(LAS unsigned char* lds, const bf16* PROJ, bf16* MIX, const float* lq1, const float* lk1, const float* lq2, const float* lk2,
;                                            const float* norm_g, float lambda_init, int G, int wave_s) {
;     ...
;             __syncthreads();
;         }
;     }
; }
.LBB0_905:
	s_setprio 0
	v_readlane_b32 s78, v254, 46
	v_readlane_b32 s84, v254, 49
	v_readlane_b32 s86, v254, 51
	v_readlane_b32 s79, v254, 47
	s_movk_i32 s82, 0x1600
	v_readlane_b32 s85, v254, 50
	v_readlane_b32 s87, v254, 52
	s_movk_i32 s83, 0xb1
	s_movk_i32 s77, 0xfff
	s_mov_b64 s[62:63], 0x4000

; #define LAS __attribute__((address_space(3)))
; __device__ __forceinline__ void s5_phase(LAS unsigned char* lds, const bf16* PROJ, const float* a_re, const float* a_im, const float* b_re, const float* b_im, const float* c_re, const float* c_im, ...
;     ...
;         for (int half = 0; half < 2; ++half) {
;             __syncthreads();
;             const size_t row0 = (size_t)b * SEQ + 1024 * half;
; #pragma unroll
;             for (int k = 0; k < 4; ++k) { const int idx = tid + 512 * k, tok = idx >> 1, hf = idx & 1;
;                 *(LAS v4u*)(UL + (tok >> 4) * 528 + ((tok & 15) * 16 + 8 * hf) * 2) = upre[k]; }
;             if (half == 0) {
; #pragma unroll
;                 for (int k = 0; k < 4; ++k) { const int idx = tid + 512 * k, tok = idx >> 1, hf = idx & 1; upre[k] = *(const v4u*)(PROJ + ((size_t)b * SEQ + 1024 + tok) * PLD + 4096 + 16 * g + 8 * hf); } }
.LBB0_1376:
	s_xor_b64 s[38:39], s[42:43], -1
	s_and_b64 vcc, exec, s[38:39]
	s_mov_b64 s[42:43], -1
	s_barrier
	s_waitcnt vmcnt(11)
	ds_write_b128 v221, v[4:7]
	s_waitcnt vmcnt(10)
	ds_write_b128 v244, v[8:11]
	s_waitcnt vmcnt(9)
	ds_write_b128 v245, v[12:15]
	s_waitcnt vmcnt(8)
	ds_write_b128 v246, v[16:19]
	s_cbranch_vccz .LBB0_1379
	s_mov_b64 s[42:43], 0
	s_andn2_b64 vcc, exec, s[78:79]
	s_mov_b64 s[40:41], 0
	s_cbranch_vccnz .LBB0_1379
	global_load_dwordx4 v[4:7], v[186:187], off
	global_load_dwordx4 v[8:11], v[188:189], off
	global_load_dwordx4 v[12:15], v[190:191], off
	global_load_dwordx4 v[16:19], v[192:193], off
	s_mov_b64 s[40:41], -1
